# phase 4: half of the workgroups run the compress-MLP second-layer loop before the LRU rescan loop (overlap of streaming and compute-bound loops across the chip)
# baseline (speedup 1.0000x reference)
; __global__ void __launch_bounds__(512, 2) fwd_megakernel(Params PK) {
;     ...
;         } else if (ph == 4) {
;             { const unsigned* LRW = (const unsigned*)(ws + WS_LRA); const float* AGP = (const float*)(ws + WS_AGG); const float* AGH = AGP + 128 * 1024;
;                 bf16_t* Ob = (bf16_t*)(ws + WS_O) + (size_t)1 * MT * DBR;
;                 for (size_t id = gtid; id < (size_t)128 * 1024; id += gstride) { const int ch = (int)(id & 1023), bc = (int)(id >> 10), b = bc >> 5, ck = bc & 31; const size_t base = (size_t)bc * 128 * DBR + ch;
;                     float h = 0.f; const float sc = fmaxf(1.0f - __expf(-((const float*)(ws + WS_PEW1))[512 + ch]), 1e-30f) * (1.0f / 65535.0f);
.LBB0_754:
	s_andn2_b64 vcc, exec, s[0:1]
	s_cbranch_vccnz .LBB0_769
	s_mov_b64 s[0:1], 0x20000
	v_cmp_gt_u64_e32 vcc, s[0:1], v[166:167]
	s_and_saveexec_b64 s[0:1], vcc
	s_cbranch_execz .LBB0_768
	s_bfe_u32 s46, s2, 0x10003
	s_cmp_eq_u32 s46, 1
	s_cbranch_scc1 .Lp4_B
.Lp4_A:
	s_add_u32 s4, s68, 0xb201800
	s_addc_u32 s5, s69, 0
	s_add_u32 s6, s68, 0x33303000
	v_readlane_b32 s8, v253, 59
	s_addc_u32 s7, s69, 0
	v_mov_b64_e32 v[2:3], v[166:167]
	v_add_u16_e32 v16, s8, v168
	s_mov_b64 s[8:9], 0

; __device__ __forceinline__ unsigned cvt_pk_bf16(float lo, float hi) { unsigned r; asm("v_cvt_pk_bf16_f32 %0, %1, %2" : "=v"(r) : "v"(lo), "v"(hi)); return r; }
; __device__ __forceinline__ float bfhi(unsigned w) { return __uint_as_float(w & 0xffff0000u); }
; __device__ __forceinline__ float bf2f(bf16_t v) { return __uint_as_float(((unsigned)v) << 16); }
; __global__ void __launch_bounds__(512, 2) fwd_megakernel(Params PK) {
;     ...
; #pragma unroll 8
;                     for (int t = 0; t < 128; ++t) { const unsigned w = LRW[base + (size_t)t * DBR]; const float a = 1.0f - (float)(w & 0xffffu) * sc, g = bfhi(w); h = a * h + g;
;                         const float sg = bf2f(Hh[((size_t)bc * 128 + t) * LDH + C_GB + ch]);
;                         Ob[base + (size_t)t * DBR] = (bf16_t)(cvt_pk_bf16(h * sg, 0.f) & 0xffffu); } } }
.LBB0_762:
	v_add_u32_e32 v56, 0x20e04000, v8
	v_add_u32_e32 v40, 0xb205000, v4
	global_load_dword v24, v56, s[68:69] offset:-4096
	global_load_ushort v40, v40, s[68:69]
	v_add_u32_e32 v41, 0xb20a600, v4
	global_load_dword v25, v56, s[68:69]
	global_load_ushort v41, v41, s[68:69]
	v_add_u32_e32 v57, 0x20e06000, v8
	v_add_u32_e32 v42, 0xb20fc00, v4
	global_load_dword v26, v57, s[68:69] offset:-4096
	global_load_ushort v42, v42, s[68:69]
	v_add_u32_e32 v43, 0xb215200, v4
	global_load_dword v27, v57, s[68:69]
	global_load_ushort v43, v43, s[68:69]
	v_add_u32_e32 v58, 0x20e08000, v8
	v_add_u32_e32 v44, 0xb21a800, v4
	global_load_dword v28, v58, s[68:69] offset:-4096
	global_load_ushort v44, v44, s[68:69]
	v_add_u32_e32 v45, 0xb21fe00, v4
	global_load_dword v29, v58, s[68:69]
	global_load_ushort v45, v45, s[68:69]
	v_add_u32_e32 v59, 0x20e0a000, v8
	v_add_u32_e32 v46, 0xb225400, v4
	global_load_dword v30, v59, s[68:69] offset:-4096
	global_load_ushort v46, v46, s[68:69]
	v_add_u32_e32 v47, 0xb22aa00, v4
	global_load_dword v31, v59, s[68:69]
	global_load_ushort v47, v47, s[68:69]
	v_add_u32_e32 v60, 0x20e0c000, v8
	v_add_u32_e32 v48, 0xb230000, v4
	global_load_dword v32, v60, s[68:69] offset:-4096
	global_load_ushort v48, v48, s[68:69]
	v_add_u32_e32 v49, 0xb235600, v4
	global_load_dword v33, v60, s[68:69]
	global_load_ushort v49, v49, s[68:69]
	v_add_u32_e32 v61, 0x20e0e000, v8
	v_add_u32_e32 v50, 0xb23ac00, v4
	global_load_dword v34, v61, s[68:69] offset:-4096
	global_load_ushort v50, v50, s[68:69]
	v_add_u32_e32 v51, 0xb240200, v4
	global_load_dword v35, v61, s[68:69]
	global_load_ushort v51, v51, s[68:69]
	v_add_u32_e32 v62, 0x20e10000, v8
	v_add_u32_e32 v52, 0xb245800, v4
	global_load_dword v36, v62, s[68:69] offset:-4096
	global_load_ushort v52, v52, s[68:69]
	v_add_u32_e32 v53, 0xb24ae00, v4
	global_load_dword v37, v62, s[68:69]
	global_load_ushort v53, v53, s[68:69]
	v_add_u32_e32 v63, 0x20e12000, v8
	v_add_u32_e32 v54, 0xb250400, v4
	global_load_dword v38, v63, s[68:69] offset:-4096
	global_load_ushort v54, v54, s[68:69]
	v_add_u32_e32 v55, 0xb255a00, v4
	global_load_dword v39, v63, s[68:69]
	global_load_ushort v55, v55, s[68:69]
	v_add_u32_e32 v8, 0x10000, v8
	v_add_u32_e32 v4, 0x56000, v4
	s_add_i32 s12, s12, -16
	v_add_u32_e32 v22, 0x2ae04000, v6
	s_waitcnt vmcnt(30)
	v_cvt_f32_u32_sdwa v21, v24 dst_sel:DWORD dst_unused:UNUSED_PAD src0_sel:WORD_0
	v_and_b32_e32 v17, 0xffff0000, v24
	v_fma_f32 v21, -v0, v21, 1.0
	v_fmac_f32_e32 v17, v14, v21
	v_lshlrev_b32_e32 v40, 16, v40
	v_mul_f32_e32 v40, v17, v40
	v_cvt_pk_bf16_f32 v40, v40, v1
	global_store_short v22, v40, s[68:69] offset:-4096
	s_waitcnt vmcnt(29)
	v_cvt_f32_u32_sdwa v21, v25 dst_sel:DWORD dst_unused:UNUSED_PAD src0_sel:WORD_0
	v_and_b32_e32 v14, 0xffff0000, v25
	v_fma_f32 v21, -v0, v21, 1.0
	v_fmac_f32_e32 v14, v17, v21
	v_lshlrev_b32_e32 v41, 16, v41
	v_mul_f32_e32 v41, v14, v41
	v_cvt_pk_bf16_f32 v41, v41, v1
	global_store_short v22, v41, s[68:69] offset:-2048
	s_waitcnt vmcnt(28)
	v_cvt_f32_u32_sdwa v21, v26 dst_sel:DWORD dst_unused:UNUSED_PAD src0_sel:WORD_0
	v_and_b32_e32 v17, 0xffff0000, v26
	v_fma_f32 v21, -v0, v21, 1.0
	v_fmac_f32_e32 v17, v14, v21
	v_lshlrev_b32_e32 v42, 16, v42
	v_mul_f32_e32 v42, v17, v42
	v_cvt_pk_bf16_f32 v42, v42, v1
	global_store_short v22, v42, s[68:69]
	s_waitcnt vmcnt(27)
	v_cvt_f32_u32_sdwa v21, v27 dst_sel:DWORD dst_unused:UNUSED_PAD src0_sel:WORD_0
	v_and_b32_e32 v14, 0xffff0000, v27
	v_fma_f32 v21, -v0, v21, 1.0
	v_fmac_f32_e32 v14, v17, v21
	v_lshlrev_b32_e32 v43, 16, v43
	v_mul_f32_e32 v43, v14, v43
	v_cvt_pk_bf16_f32 v43, v43, v1
	global_store_short v22, v43, s[68:69] offset:2048
	v_add_u32_e32 v22, 0x2ae06000, v6
	s_waitcnt vmcnt(26)
	v_cvt_f32_u32_sdwa v21, v28 dst_sel:DWORD dst_unused:UNUSED_PAD src0_sel:WORD_0
	v_and_b32_e32 v17, 0xffff0000, v28
	v_fma_f32 v21, -v0, v21, 1.0
	v_fmac_f32_e32 v17, v14, v21
	v_lshlrev_b32_e32 v44, 16, v44
	v_mul_f32_e32 v44, v17, v44
	v_cvt_pk_bf16_f32 v44, v44, v1
	global_store_short v22, v44, s[68:69] offset:-4096
	s_waitcnt vmcnt(25)
; __device__ __forceinline__ unsigned cvt_pk_bf16(float lo, float hi) { unsigned r; asm("v_cvt_pk_bf16_f32 %0, %1, %2" : "=v"(r) : "v"(lo), "v"(hi)); return r; }
; __device__ __forceinline__ float bfhi(unsigned w) { return __uint_as_float(w & 0xffff0000u); }
; __device__ __forceinline__ float bf2f(bf16_t v) { return __uint_as_float(((unsigned)v) << 16); }
; __global__ void __launch_bounds__(512, 2) fwd_megakernel(Params PK) {
;     ...
; #pragma unroll 8
;                     for (int t = 0; t < 128; ++t) { const unsigned w = LRW[base + (size_t)t * DBR]; const float a = 1.0f - (float)(w & 0xffffu) * sc, g = bfhi(w); h = a * h + g;
;                         const float sg = bf2f(Hh[((size_t)bc * 128 + t) * LDH + C_GB + ch]);
;                         Ob[base + (size_t)t * DBR] = (bf16_t)(cvt_pk_bf16(h * sg, 0.f) & 0xffffu); } } }
;             { const bf16_t* HID = (const bf16_t*)(ws + WS_HID); bf16_t* KCV = (bf16_t*)(ws + WS_KCV);
;                 for (size_t id = gtid; id < (size_t)2 * 4096 * 16; id += gstride) { const int e4 = (int)(id & 15) * 4, row = (int)((id >> 4) & 4095), kv = (int)(id >> 16);
	v_cvt_f32_u32_sdwa v21, v29 dst_sel:DWORD dst_unused:UNUSED_PAD src0_sel:WORD_0
	v_and_b32_e32 v14, 0xffff0000, v29
	v_fma_f32 v21, -v0, v21, 1.0
	v_fmac_f32_e32 v14, v17, v21
	v_lshlrev_b32_e32 v45, 16, v45
	v_mul_f32_e32 v45, v14, v45
	v_cvt_pk_bf16_f32 v45, v45, v1
	global_store_short v22, v45, s[68:69] offset:-2048
	s_waitcnt vmcnt(24)
	v_cvt_f32_u32_sdwa v21, v30 dst_sel:DWORD dst_unused:UNUSED_PAD src0_sel:WORD_0
	v_and_b32_e32 v17, 0xffff0000, v30
	v_fma_f32 v21, -v0, v21, 1.0
	v_fmac_f32_e32 v17, v14, v21
	v_lshlrev_b32_e32 v46, 16, v46
	v_mul_f32_e32 v46, v17, v46
	v_cvt_pk_bf16_f32 v46, v46, v1
	global_store_short v22, v46, s[68:69]
	s_waitcnt vmcnt(23)
	v_cvt_f32_u32_sdwa v21, v31 dst_sel:DWORD dst_unused:UNUSED_PAD src0_sel:WORD_0
	v_and_b32_e32 v14, 0xffff0000, v31
	v_fma_f32 v21, -v0, v21, 1.0
	v_fmac_f32_e32 v14, v17, v21
	v_lshlrev_b32_e32 v47, 16, v47
	v_mul_f32_e32 v47, v14, v47
	v_cvt_pk_bf16_f32 v47, v47, v1
	global_store_short v22, v47, s[68:69] offset:2048
	v_add_u32_e32 v22, 0x2ae08000, v6
	s_waitcnt vmcnt(22)
	v_cvt_f32_u32_sdwa v21, v32 dst_sel:DWORD dst_unused:UNUSED_PAD src0_sel:WORD_0
	v_and_b32_e32 v17, 0xffff0000, v32
	v_fma_f32 v21, -v0, v21, 1.0
	v_fmac_f32_e32 v17, v14, v21
	v_lshlrev_b32_e32 v48, 16, v48
	v_mul_f32_e32 v48, v17, v48
	v_cvt_pk_bf16_f32 v48, v48, v1
	global_store_short v22, v48, s[68:69] offset:-4096
	s_waitcnt vmcnt(21)
	v_cvt_f32_u32_sdwa v21, v33 dst_sel:DWORD dst_unused:UNUSED_PAD src0_sel:WORD_0
	v_and_b32_e32 v14, 0xffff0000, v33
	v_fma_f32 v21, -v0, v21, 1.0
	v_fmac_f32_e32 v14, v17, v21
	v_lshlrev_b32_e32 v49, 16, v49
	v_mul_f32_e32 v49, v14, v49
	v_cvt_pk_bf16_f32 v49, v49, v1
	global_store_short v22, v49, s[68:69] offset:-2048
	s_waitcnt vmcnt(20)
	v_cvt_f32_u32_sdwa v21, v34 dst_sel:DWORD dst_unused:UNUSED_PAD src0_sel:WORD_0
	v_and_b32_e32 v17, 0xffff0000, v34
	v_fma_f32 v21, -v0, v21, 1.0
	v_fmac_f32_e32 v17, v14, v21
	v_lshlrev_b32_e32 v50, 16, v50
	v_mul_f32_e32 v50, v17, v50
	v_cvt_pk_bf16_f32 v50, v50, v1
	global_store_short v22, v50, s[68:69]
	s_waitcnt vmcnt(19)
	v_cvt_f32_u32_sdwa v21, v35 dst_sel:DWORD dst_unused:UNUSED_PAD src0_sel:WORD_0
	v_and_b32_e32 v14, 0xffff0000, v35
	v_fma_f32 v21, -v0, v21, 1.0
	v_fmac_f32_e32 v14, v17, v21
	v_lshlrev_b32_e32 v51, 16, v51
	v_mul_f32_e32 v51, v14, v51
	v_cvt_pk_bf16_f32 v51, v51, v1
	global_store_short v22, v51, s[68:69] offset:2048
	v_add_u32_e32 v22, 0x2ae0a000, v6
	s_waitcnt vmcnt(18)
	v_cvt_f32_u32_sdwa v21, v36 dst_sel:DWORD dst_unused:UNUSED_PAD src0_sel:WORD_0
	v_and_b32_e32 v17, 0xffff0000, v36
	v_fma_f32 v21, -v0, v21, 1.0
	v_fmac_f32_e32 v17, v14, v21
	v_lshlrev_b32_e32 v52, 16, v52
	v_mul_f32_e32 v52, v17, v52
	v_cvt_pk_bf16_f32 v52, v52, v1
	global_store_short v22, v52, s[68:69] offset:-4096
	s_waitcnt vmcnt(17)
	v_cvt_f32_u32_sdwa v21, v37 dst_sel:DWORD dst_unused:UNUSED_PAD src0_sel:WORD_0
	v_and_b32_e32 v14, 0xffff0000, v37
	v_fma_f32 v21, -v0, v21, 1.0
	v_fmac_f32_e32 v14, v17, v21
	v_lshlrev_b32_e32 v53, 16, v53
	v_mul_f32_e32 v53, v14, v53
	v_cvt_pk_bf16_f32 v53, v53, v1
	global_store_short v22, v53, s[68:69] offset:-2048
	s_waitcnt vmcnt(16)
	v_cvt_f32_u32_sdwa v21, v38 dst_sel:DWORD dst_unused:UNUSED_PAD src0_sel:WORD_0
	v_and_b32_e32 v17, 0xffff0000, v38
	v_fma_f32 v21, -v0, v21, 1.0
	v_fmac_f32_e32 v17, v14, v21
	v_lshlrev_b32_e32 v54, 16, v54
	v_mul_f32_e32 v54, v17, v54
	v_cvt_pk_bf16_f32 v54, v54, v1
	global_store_short v22, v54, s[68:69]
	s_waitcnt vmcnt(15)
	v_cvt_f32_u32_sdwa v21, v39 dst_sel:DWORD dst_unused:UNUSED_PAD src0_sel:WORD_0
	v_and_b32_e32 v14, 0xffff0000, v39
	v_fma_f32 v21, -v0, v21, 1.0
	v_fmac_f32_e32 v14, v17, v21
	v_lshlrev_b32_e32 v55, 16, v55
	v_mul_f32_e32 v55, v14, v55
	v_cvt_pk_bf16_f32 v55, v55, v1
	global_store_short v22, v55, s[68:69] offset:2048
	v_add_u32_e32 v6, 0x8000, v6
	s_cmp_eq_u32 s12, 0
	s_cbranch_scc0 .LBB0_762
	v_lshl_add_u64 v[2:3], v[2:3], 0, s[38:39]
	s_mov_b64 s[12:13], 0x1ffff
	v_cmp_lt_u64_e32 vcc, s[12:13], v[2:3]
	v_readlane_b32 s12, v253, 60
	s_or_b64 s[8:9], vcc, s[8:9]
	s_nop 0
	v_subrev_u16_e32 v16, s12, v16
	s_andn2_b64 exec, exec, s[8:9]
	s_cbranch_execnz .LBB0_757
	s_or_b64 exec, exec, s[8:9]
	s_cmp_eq_u32 s46, 3
	s_cbranch_scc1 .LBB0_768
	s_branch .Lp4_B2

; __global__ void __launch_bounds__(512, 2) fwd_megakernel(Params PK) {
;     ...
;             { const bf16_t* HID = (const bf16_t*)(ws + WS_HID); bf16_t* KCV = (bf16_t*)(ws + WS_KCV);
;                 for (size_t id = gtid; id < (size_t)2 * 4096 * 16; id += gstride) { const int e4 = (int)(id & 15) * 4, row = (int)((id >> 4) & 4095), kv = (int)(id >> 16);
;                     const float* w2 = P.in[19 + kv] + (size_t)l * 256 * 64; const bf16_t* hr = HID + ((size_t)kv * 4096 + row) * 256; f32x4 a = (f32x4){0.f, 0.f, 0.f, 0.f};
.Lp4_B2:
	s_add_u32 s4, s68, 0x33203000
	v_readlane_b32 s6, v255, 43
	s_addc_u32 s5, s69, 0
	v_readlane_b32 s7, v255, 44
	s_and_b64 s[6:7], s[6:7], exec
	v_readlane_b32 s8, v253, 62
	s_cselect_b32 s12, 0x10000, 0
	s_add_u32 s6, s68, 0x32e0301c
	v_readlane_b32 s9, v253, 63
	s_addc_u32 s7, s69, 0
	v_mov_b64_e32 v[8:9], v[166:167]
	v_lshl_add_u64 v[6:7], v[168:169], 2, s[8:9]
	s_mov_b64 s[8:9], 0

; __device__ __forceinline__ unsigned cvt_pk_bf16(float lo, float hi) { unsigned r; asm("v_cvt_pk_bf16_f32 %0, %1, %2" : "=v"(r) : "v"(lo), "v"(hi)); return r; }
; __device__ __forceinline__ float bfhi(unsigned w) { return __uint_as_float(w & 0xffff0000u); }
; __device__ __forceinline__ float bf2f(bf16_t v) { return __uint_as_float(((unsigned)v) << 16); }
; __global__ void __launch_bounds__(512, 2) fwd_megakernel(Params PK) {
;     ...
;             { const unsigned* LRW = (const unsigned*)(ws + WS_LRA); const float* AGP = (const float*)(ws + WS_AGG); const float* AGH = AGP + 128 * 1024;
;                 bf16_t* Ob = (bf16_t*)(ws + WS_O) + (size_t)1 * MT * DBR;
;                 for (size_t id = gtid; id < (size_t)128 * 1024; id += gstride) { const int ch = (int)(id & 1023), bc = (int)(id >> 10), b = bc >> 5, ck = bc & 31; const size_t base = (size_t)bc * 128 * DBR + ch;
;                     float h = 0.f; const float sc = fmaxf(1.0f - __expf(-((const float*)(ws + WS_PEW1))[512 + ch]), 1e-30f) * (1.0f / 65535.0f);
;                     for (int j = 0; j < ck; ++j) { const size_t a = (size_t)(b * 32 + j) * 1024 + ch; h = AGP[a] * h + AGH[a]; }
; #pragma unroll 8
;                     for (int t = 0; t < 128; ++t) { const unsigned w = LRW[base + (size_t)t * DBR]; const float a = 1.0f - (float)(w & 0xffffu) * sc, g = bfhi(w); h = a * h + g;
;                         const float sg = bf2f(Hh[((size_t)bc * 128 + t) * LDH + C_GB + ch]);
;                         Ob[base + (size_t)t * DBR] = (bf16_t)(cvt_pk_bf16(h * sg, 0.f) & 0xffffu); } } }
;             { const bf16_t* HID = (const bf16_t*)(ws + WS_HID); bf16_t* KCV = (bf16_t*)(ws + WS_KCV);
;                 for (size_t id = gtid; id < (size_t)2 * 4096 * 16; id += gstride) { const int e4 = (int)(id & 15) * 4, row = (int)((id >> 4) & 4095), kv = (int)(id >> 16);
.LBB0_768:
	s_cmp_eq_u32 s46, 1
	s_cbranch_scc0 .Lp4_end
	s_or_b64 exec, exec, s[8:9]
	s_mov_b32 s46, 3
	s_branch .Lp4_A
